# L2 warm-up: before waiting at the seam in front of P2/P5/P6 each thread touches two lines of the first four K-tiles of the phase's first weight tile
# baseline (speedup 1.0000x reference)
.LBB0_215:
	s_and_b64 vcc, exec, s[4:5]
	s_cbranch_vccz .LBB0_232
	s_waitcnt vmcnt(0)
	s_barrier
	s_lshr_b32 s96, s2, 6
	s_lshl_b32 s96, s96, 19
	s_add_u32 s96, s70, s96
	s_addc_u32 s97, s71, 0
	v_lshrrev_b32_e32 v247, 1, v0
	v_and_b32_e32 v248, 1, v0
	v_lshlrev_b32_e32 v247, 11, v247
	v_lshl_or_b32 v247, v248, 8, v247
	global_load_dword v248, v247, s[96:97]
	global_load_dword v247, v247, s[96:97] offset:128
	s_and_saveexec_b64 s[4:5], s[58:59]
	s_cbranch_execz .LBB0_231
	v_readlane_b32 s0, v250, 13
	s_lshl_b32 s6, s0, 6
	s_ashr_i32 s7, s6, 31
	s_lshl_b64 s[6:7], s[6:7], 2
	s_mov_b64 s[22:23], exec
	s_add_u32 s0, s34, s6
	s_addc_u32 s7, s35, s7
	v_mbcnt_lo_u32_b32 v2, s22, 0
	s_add_u32 s6, s0, 0x40000
	v_mbcnt_hi_u32_b32 v2, s23, v2
	s_addc_u32 s7, s7, 0
	v_cmp_eq_u32_e32 vcc, 0, v2
	s_and_saveexec_b64 s[36:37], vcc
	s_cbranch_execz .LBB0_219
	s_bcnt1_i32_b64 s0, s[22:23]
	v_mov_b32_e32 v2, 0
	v_mov_b32_e32 v3, s0
	global_atomic_add v2, v3, s[6:7]

.LBB0_740:
	s_and_b64 vcc, exec, s[6:7]
	s_cbranch_vccz .LBB0_757
	s_waitcnt vmcnt(0)
	s_waitcnt lgkmcnt(0)
	s_barrier
	s_lshr_b32 s0, s2, 6
	s_lshl_b32 s0, s0, 19
	s_add_u32 s0, s64, s0
	s_addc_u32 s1, s65, 0
	v_lshrrev_b32_e32 v247, 1, v0
	v_and_b32_e32 v248, 1, v0
	v_lshlrev_b32_e32 v247, 11, v247
	v_lshl_or_b32 v247, v248, 8, v247
	global_load_dword v248, v247, s[0:1]
	global_load_dword v247, v247, s[0:1] offset:128
	s_and_saveexec_b64 s[6:7], s[58:59]
	s_cbranch_execz .LBB0_756
	v_readlane_b32 s0, v250, 13
	s_lshl_b32 s0, s0, 6
	s_ashr_i32 s1, s0, 31
	s_lshl_b64 s[0:1], s[0:1], 2
	s_mov_b64 s[10:11], exec
	s_add_u32 s0, s34, s0
	s_addc_u32 s1, s35, s1
	v_mbcnt_lo_u32_b32 v2, s10, 0
	s_add_u32 s8, s0, 0x40000
	v_mbcnt_hi_u32_b32 v2, s11, v2
	s_addc_u32 s9, s1, 0
	v_cmp_eq_u32_e32 vcc, 0, v2
	s_and_saveexec_b64 s[12:13], vcc
	s_cbranch_execz .LBB0_744
	s_bcnt1_i32_b64 s0, s[10:11]
	v_mov_b32_e32 v2, 0
	v_mov_b32_e32 v3, s0
	global_atomic_add v2, v3, s[8:9]

.LBB0_830:
	s_and_b64 vcc, exec, s[6:7]
	s_cbranch_vccz .LBB0_847
	s_waitcnt vmcnt(0)
	s_waitcnt vmcnt(0) lgkmcnt(0)
	s_barrier
	s_lshr_b32 s0, s2, 6
	s_mul_i32 s0, s0, 0x160000
	s_add_u32 s0, s54, s0
	s_addc_u32 s1, s55, 0
	v_lshrrev_b32_e32 v247, 1, v0
	v_and_b32_e32 v248, 1, v0
	v_mul_u32_u24_e32 v247, 0x1600, v247
	v_lshl_or_b32 v247, v248, 8, v247
	global_load_dword v248, v247, s[0:1]
	global_load_dword v247, v247, s[0:1] offset:128
	s_and_saveexec_b64 s[6:7], s[58:59]
	s_cbranch_execz .LBB0_846
	v_readlane_b32 s0, v250, 13
	s_lshl_b32 s0, s0, 6
	s_ashr_i32 s1, s0, 31
	s_lshl_b64 s[0:1], s[0:1], 2
	s_mov_b64 s[10:11], exec
	s_add_u32 s0, s34, s0
	s_addc_u32 s1, s35, s1
	v_mbcnt_lo_u32_b32 v2, s10, 0
	s_add_u32 s0, s0, 0x40000
	v_mbcnt_hi_u32_b32 v2, s11, v2
	s_addc_u32 s1, s1, 0
	v_cmp_eq_u32_e32 vcc, 0, v2
	s_and_saveexec_b64 s[12:13], vcc
	s_cbranch_execz .LBB0_834
	s_bcnt1_i32_b64 s10, s[10:11]
	v_mov_b32_e32 v2, 0
	v_mov_b32_e32 v3, s10
	global_atomic_add v2, v3, s[0:1]
